# gdn_post token loop: all loads of a token issued up front, DPP wave reduction instead of ds_bpermute
# speedup vs baseline: 1.0062x; 1.0062x over previous
; DI unsigned pk2(float lo, float hi) { f32x2 v = {lo, hi}; bf16x2_t b = __builtin_convertvector(v, bf16x2_t); return __builtin_bit_cast(unsigned, b); }
; DI float frsq(float x) { return __builtin_amdgcn_rsqf(x); }
; DI float siluf_(float x) { return x * frcp(1.f + __expf(-x)); }
; DI void gdn_post_row(const float* ORAW, const float* P, const float* norm_g, bf16* YCAT, long tg, int lane) {
;     const f32x2 g2 = *(const f32x2*)(norm_g + 2 * lane);
; #pragma unroll 4
;     for (int vh = 0; vh < 12; ++vh) {
;         const f32x2 o = *(const f32x2*)(ORAW + tg * MIXW + vh * 128 + 2 * lane);
;         const f32x2 z = *(const f32x2*)(P + tg * 5376 + 3072 + vh * 128 + 2 * lane);
;         const float rs = frsq(wave_sum(o.x * o.x + o.y * o.y) * (1.f / 128.f) + 1e-6f);
;         *(unsigned*)(YCAT + tg * DM + vh * 128 + 2 * lane) = pk2(o.x * rs * g2.x * siluf_(z.x), o.y * rs * g2.y * siluf_(z.y));
;     }
; }
; DI void phase_gdn_post(const Ctx& c) {
;     const float* ng = INP(29);
;     for (long m = c.gw; m < T; m += c.NGW) gdn_post_row(c.ORAW, c.P, ng, c.YCAT, m, c.lane);
; }
.LBB0_1020:
	s_andn2_b64 vcc, exec, s[4:5]
	s_cbranch_vccnz .LBB0_1093
	v_readlane_b32 s12, v255, 0
	v_readlane_b32 s13, v255, 1
	s_mov_b64 s[6:7], s[12:13]
	s_waitcnt vmcnt(0)
	v_mov_b32_e32 v2, v240
	s_mov_b32 s2, s56
	s_mov_b32 s1, s47
	s_load_dwordx4 s[8:11], s[12:13], 0x100
	s_lshl_b32 s2, s2, 3
	v_readfirstlane_b32 s1, v2
	s_ashr_i32 s4, s1, 6
	s_add_i32 s4, s4, s2
	s_waitcnt lgkmcnt(0)
	s_mov_b32 s1, s10
	s_cmpk_gt_i32 s4, 0x3fff
	s_cbranch_scc1 .LBB0_1026
	v_and_b32_e32 v0, 64, v254
	v_add_u32_e32 v0, 64, v0
	v_xor_b32_e32 v1, 1, v254
	v_cmp_lt_i32_e32 vcc, v1, v0
	s_load_dwordx2 s[8:9], s[6:7], 0xe8
	s_load_dwordx2 s[12:13], s[6:7], 0xf8
	v_cndmask_b32_e32 v1, v254, v1, vcc
	v_lshlrev_b32_e32 v12, 2, v1
	v_xor_b32_e32 v1, 2, v254
	v_cmp_lt_i32_e32 vcc, v1, v0
	s_lshl_b32 s6, s1, 3
	s_ashr_i32 s5, s4, 31
	v_cndmask_b32_e32 v1, v254, v1, vcc
	v_lshlrev_b32_e32 v13, 2, v1
	v_xor_b32_e32 v1, 4, v254
	v_cmp_lt_i32_e32 vcc, v1, v0
	s_ashr_i32 s7, s6, 31
	v_and_b32_e32 v4, 63, v2
	v_cndmask_b32_e32 v1, v254, v1, vcc
	v_lshlrev_b32_e32 v14, 2, v1
	v_xor_b32_e32 v1, 8, v254
	v_cmp_lt_i32_e32 vcc, v1, v0
	s_mul_i32 s10, s4, 0x1800
	s_mul_hi_i32 s2, s4, 0x1800
	v_cndmask_b32_e32 v1, v254, v1, vcc
	v_lshlrev_b32_e32 v15, 2, v1
	v_xor_b32_e32 v1, 16, v254
	v_cmp_lt_i32_e32 vcc, v1, v0
	s_mul_i32 s14, s4, 0x5400
	s_nop 0
	v_cndmask_b32_e32 v1, v254, v1, vcc
	v_lshlrev_b32_e32 v16, 2, v1
	v_xor_b32_e32 v1, 32, v254
	v_cmp_lt_i32_e32 vcc, v1, v0
	s_nop 1
	v_cndmask_b32_e32 v0, v254, v1, vcc
	v_lshlrev_b32_e32 v17, 2, v0
	v_lshlrev_b32_e32 v0, 3, v2
	v_and_b32_e32 v128, 0x1f8, v0
	s_waitcnt lgkmcnt(0)
	v_lshl_add_u64 v[0:1], s[8:9], 0, v[128:129]
	s_lshl_b64 s[8:9], s[4:5], 12
	s_add_u32 s8, s12, s8
	v_lshlrev_b32_e32 v128, 2, v4
	s_addc_u32 s9, s13, s9
	v_lshl_add_u64 v[2:3], s[8:9], 0, v[128:129]
	s_mov_b64 s[8:9], 0x12a00200
	v_lshl_add_u64 v[2:3], v[2:3], 0, s[8:9]
	s_lshl_b64 s[8:9], s[6:7], 12
	s_add_u32 s10, s12, s10
	s_addc_u32 s11, s13, s2
	s_mul_hi_i32 s2, s4, 0x5400
	s_add_u32 s12, s12, s14
	v_lshlrev_b32_e32 v128, 3, v4
	s_addc_u32 s13, s13, s2
	v_lshl_add_u64 v[4:5], s[10:11], 0, v[128:129]
	s_mov_b64 s[10:11], 0x2ea00400
	v_lshl_add_u64 v[6:7], s[12:13], 0, v[128:129]
	s_mov_b64 s[12:13], 0x18a03400
	v_lshl_add_u64 v[4:5], v[4:5], 0, s[10:11]
	s_mul_i32 s10, s1, 0xc000
	s_mul_hi_i32 s11, s6, 0x1800
	v_lshl_add_u64 v[6:7], v[6:7], 0, s[12:13]
	s_mul_i32 s12, s1, 0x2a000
	s_mul_hi_i32 s13, s6, 0x5400
	global_load_dwordx2 v[26:27], v[0:1], off
.LBB0_1023:
	s_mov_b64 s[14:15], 0x800
	s_mov_b64 s[16:17], 0x1000
	v_lshl_add_u64 v[18:19], v[4:5], 0, s[14:15]
	v_lshl_add_u64 v[20:21], v[4:5], 0, s[16:17]
	v_lshl_add_u64 v[22:23], v[6:7], 0, s[14:15]
	v_lshl_add_u64 v[24:25], v[6:7], 0, s[16:17]
	global_load_dwordx2 v[32:33], v[4:5], off offset:-1024
	global_load_dwordx2 v[56:57], v[6:7], off offset:-1024
	global_load_dwordx2 v[34:35], v[4:5], off offset:-512
	global_load_dwordx2 v[58:59], v[6:7], off offset:-512
	global_load_dwordx2 v[36:37], v[4:5], off
	global_load_dwordx2 v[60:61], v[6:7], off
	global_load_dwordx2 v[38:39], v[4:5], off offset:512
	global_load_dwordx2 v[62:63], v[6:7], off offset:512
	global_load_dwordx2 v[40:41], v[18:19], off offset:-1024
	global_load_dwordx2 v[64:65], v[22:23], off offset:-1024
	global_load_dwordx2 v[42:43], v[18:19], off offset:-512
	global_load_dwordx2 v[66:67], v[22:23], off offset:-512
	global_load_dwordx2 v[44:45], v[18:19], off
	global_load_dwordx2 v[68:69], v[22:23], off
	global_load_dwordx2 v[46:47], v[18:19], off offset:512
	global_load_dwordx2 v[70:71], v[22:23], off offset:512
	global_load_dwordx2 v[48:49], v[20:21], off offset:-1024
	global_load_dwordx2 v[72:73], v[24:25], off offset:-1024
	global_load_dwordx2 v[50:51], v[20:21], off offset:-512
	global_load_dwordx2 v[74:75], v[24:25], off offset:-512
	global_load_dwordx2 v[52:53], v[20:21], off
	global_load_dwordx2 v[76:77], v[24:25], off
	global_load_dwordx2 v[54:55], v[20:21], off offset:512
	global_load_dwordx2 v[78:79], v[24:25], off offset:512
	s_waitcnt vmcnt(22)
	v_mul_f32_e32 v80, v32, v32
	v_mul_f32_e32 v82, 0xbfb8aa3b, v56
	v_fmac_f32_e32 v80, v33, v33
	v_mul_f32_e32 v83, 0xbfb8aa3b, v57
	v_exp_f32_e32 v82, v82
	v_exp_f32_e32 v83, v83
	v_add_f32_dpp v80, v80, v80 quad_perm:[1,0,3,2] row_mask:0xf bank_mask:0xf bound_ctrl:1
	v_add_f32_e32 v82, 1.0, v82
	v_add_f32_e32 v83, 1.0, v83
	v_add_f32_dpp v80, v80, v80 quad_perm:[2,3,0,1] row_mask:0xf bank_mask:0xf bound_ctrl:1
	v_rcp_f32_e32 v82, v82
	v_rcp_f32_e32 v83, v83
	v_add_f32_dpp v80, v80, v80 row_half_mirror row_mask:0xf bank_mask:0xf bound_ctrl:1
	v_mul_f32_e32 v84, v32, v26
	v_mul_f32_e32 v85, v33, v27
	v_add_f32_dpp v80, v80, v80 row_ror:8 row_mask:0xf bank_mask:0xf bound_ctrl:1
	v_mul_f32_e32 v82, v56, v82
	v_mul_f32_e32 v83, v57, v83
	v_add_f32_dpp v80, v80, v80 row_bcast:15 row_mask:0xa bank_mask:0xf
	v_mul_f32_e32 v84, v84, v82
	v_mul_f32_e32 v85, v85, v83
	v_add_f32_dpp v80, v80, v80 row_bcast:31 row_mask:0xc bank_mask:0xf
	s_nop 1
	v_readlane_b32 s20, v80, 63
	s_nop 2
	v_mov_b32_e32 v81, s20
	v_fmamk_f32 v81, v81, 0x3c000000, v241
	v_rsq_f32_e32 v81, v81
	s_nop 0
	v_mul_f32_e32 v84, v84, v81
	v_mul_f32_e32 v85, v85, v81
	v_cvt_pk_bf16_f32 v84, v84, v85
	global_store_dword v[2:3], v84, off offset:-512
	s_waitcnt vmcnt(21)
; DI unsigned pk2(float lo, float hi) { f32x2 v = {lo, hi}; bf16x2_t b = __builtin_convertvector(v, bf16x2_t); return __builtin_bit_cast(unsigned, b); }
; DI float frsq(float x) { return __builtin_amdgcn_rsqf(x); }
; DI float siluf_(float x) { return x * frcp(1.f + __expf(-x)); }
; DI void gdn_post_row(const float* ORAW, const float* P, const float* norm_g, bf16* YCAT, long tg, int lane) {
;     const f32x2 g2 = *(const f32x2*)(norm_g + 2 * lane);
; #pragma unroll 4
;     for (int vh = 0; vh < 12; ++vh) {
;         const f32x2 o = *(const f32x2*)(ORAW + tg * MIXW + vh * 128 + 2 * lane);
;         const f32x2 z = *(const f32x2*)(P + tg * 5376 + 3072 + vh * 128 + 2 * lane);
;         const float rs = frsq(wave_sum(o.x * o.x + o.y * o.y) * (1.f / 128.f) + 1e-6f);
;         *(unsigned*)(YCAT + tg * DM + vh * 128 + 2 * lane) = pk2(o.x * rs * g2.x * siluf_(z.x), o.y * rs * g2.y * siluf_(z.y));
;     }
; }
	v_mul_f32_e32 v80, v34, v34
	v_mul_f32_e32 v82, 0xbfb8aa3b, v58
	v_fmac_f32_e32 v80, v35, v35
	v_mul_f32_e32 v83, 0xbfb8aa3b, v59
	v_exp_f32_e32 v82, v82
	v_exp_f32_e32 v83, v83
	v_add_f32_dpp v80, v80, v80 quad_perm:[1,0,3,2] row_mask:0xf bank_mask:0xf bound_ctrl:1
	v_add_f32_e32 v82, 1.0, v82
	v_add_f32_e32 v83, 1.0, v83
	v_add_f32_dpp v80, v80, v80 quad_perm:[2,3,0,1] row_mask:0xf bank_mask:0xf bound_ctrl:1
	v_rcp_f32_e32 v82, v82
	v_rcp_f32_e32 v83, v83
	v_add_f32_dpp v80, v80, v80 row_half_mirror row_mask:0xf bank_mask:0xf bound_ctrl:1
	v_mul_f32_e32 v84, v34, v26
	v_mul_f32_e32 v85, v35, v27
	v_add_f32_dpp v80, v80, v80 row_ror:8 row_mask:0xf bank_mask:0xf bound_ctrl:1
	v_mul_f32_e32 v82, v58, v82
	v_mul_f32_e32 v83, v59, v83
	v_add_f32_dpp v80, v80, v80 row_bcast:15 row_mask:0xa bank_mask:0xf
	v_mul_f32_e32 v84, v84, v82
	v_mul_f32_e32 v85, v85, v83
	v_add_f32_dpp v80, v80, v80 row_bcast:31 row_mask:0xc bank_mask:0xf
	s_nop 1
	v_readlane_b32 s20, v80, 63
	s_nop 2
	v_mov_b32_e32 v81, s20
	v_fmamk_f32 v81, v81, 0x3c000000, v241
	v_rsq_f32_e32 v81, v81
	s_nop 0
	v_mul_f32_e32 v84, v84, v81
	v_mul_f32_e32 v85, v85, v81
	v_cvt_pk_bf16_f32 v84, v84, v85
	global_store_dword v[2:3], v84, off offset:-256
	s_waitcnt vmcnt(20)
	v_mul_f32_e32 v80, v36, v36
	v_mul_f32_e32 v82, 0xbfb8aa3b, v60
	v_fmac_f32_e32 v80, v37, v37
	v_mul_f32_e32 v83, 0xbfb8aa3b, v61
	v_exp_f32_e32 v82, v82
	v_exp_f32_e32 v83, v83
	v_add_f32_dpp v80, v80, v80 quad_perm:[1,0,3,2] row_mask:0xf bank_mask:0xf bound_ctrl:1
	v_add_f32_e32 v82, 1.0, v82
	v_add_f32_e32 v83, 1.0, v83
	v_add_f32_dpp v80, v80, v80 quad_perm:[2,3,0,1] row_mask:0xf bank_mask:0xf bound_ctrl:1
	v_rcp_f32_e32 v82, v82
	v_rcp_f32_e32 v83, v83
	v_add_f32_dpp v80, v80, v80 row_half_mirror row_mask:0xf bank_mask:0xf bound_ctrl:1
	v_mul_f32_e32 v84, v36, v26
	v_mul_f32_e32 v85, v37, v27
	v_add_f32_dpp v80, v80, v80 row_ror:8 row_mask:0xf bank_mask:0xf bound_ctrl:1
	v_mul_f32_e32 v82, v60, v82
	v_mul_f32_e32 v83, v61, v83
	v_add_f32_dpp v80, v80, v80 row_bcast:15 row_mask:0xa bank_mask:0xf
	v_mul_f32_e32 v84, v84, v82
	v_mul_f32_e32 v85, v85, v83
	v_add_f32_dpp v80, v80, v80 row_bcast:31 row_mask:0xc bank_mask:0xf
	s_nop 1
	v_readlane_b32 s20, v80, 63
	s_nop 2
	v_mov_b32_e32 v81, s20
	v_fmamk_f32 v81, v81, 0x3c000000, v241
	v_rsq_f32_e32 v81, v81
	s_nop 0
	v_mul_f32_e32 v84, v84, v81
	v_mul_f32_e32 v85, v85, v81
	v_cvt_pk_bf16_f32 v84, v84, v85
	global_store_dword v[2:3], v84, off
	s_waitcnt vmcnt(19)
	v_mul_f32_e32 v80, v38, v38
	v_mul_f32_e32 v82, 0xbfb8aa3b, v62
	v_fmac_f32_e32 v80, v39, v39
	v_mul_f32_e32 v83, 0xbfb8aa3b, v63
	v_exp_f32_e32 v82, v82
	v_exp_f32_e32 v83, v83
	v_add_f32_dpp v80, v80, v80 quad_perm:[1,0,3,2] row_mask:0xf bank_mask:0xf bound_ctrl:1
	v_add_f32_e32 v82, 1.0, v82
	v_add_f32_e32 v83, 1.0, v83
	v_add_f32_dpp v80, v80, v80 quad_perm:[2,3,0,1] row_mask:0xf bank_mask:0xf bound_ctrl:1
	v_rcp_f32_e32 v82, v82
	v_rcp_f32_e32 v83, v83
	v_add_f32_dpp v80, v80, v80 row_half_mirror row_mask:0xf bank_mask:0xf bound_ctrl:1
	v_mul_f32_e32 v84, v38, v26
	v_mul_f32_e32 v85, v39, v27
	v_add_f32_dpp v80, v80, v80 row_ror:8 row_mask:0xf bank_mask:0xf bound_ctrl:1
	v_mul_f32_e32 v82, v62, v82
	v_mul_f32_e32 v83, v63, v83
	v_add_f32_dpp v80, v80, v80 row_bcast:15 row_mask:0xa bank_mask:0xf
	v_mul_f32_e32 v84, v84, v82
	v_mul_f32_e32 v85, v85, v83
	v_add_f32_dpp v80, v80, v80 row_bcast:31 row_mask:0xc bank_mask:0xf
	s_nop 1
	v_readlane_b32 s20, v80, 63
	s_nop 2
	v_mov_b32_e32 v81, s20
	v_fmamk_f32 v81, v81, 0x3c000000, v241
	v_rsq_f32_e32 v81, v81
	s_nop 0
	v_mul_f32_e32 v84, v84, v81
	v_mul_f32_e32 v85, v85, v81
	v_cvt_pk_bf16_f32 v84, v84, v85
	global_store_dword v[2:3], v84, off offset:256
	s_waitcnt vmcnt(18)
	v_mul_f32_e32 v80, v40, v40
	v_mul_f32_e32 v82, 0xbfb8aa3b, v64
	v_fmac_f32_e32 v80, v41, v41
	v_mul_f32_e32 v83, 0xbfb8aa3b, v65
	v_exp_f32_e32 v82, v82
	v_exp_f32_e32 v83, v83
	v_add_f32_dpp v80, v80, v80 quad_perm:[1,0,3,2] row_mask:0xf bank_mask:0xf bound_ctrl:1
	v_add_f32_e32 v82, 1.0, v82
	v_add_f32_e32 v83, 1.0, v83
	v_add_f32_dpp v80, v80, v80 quad_perm:[2,3,0,1] row_mask:0xf bank_mask:0xf bound_ctrl:1
	v_rcp_f32_e32 v82, v82
	v_rcp_f32_e32 v83, v83
	v_add_f32_dpp v80, v80, v80 row_half_mirror row_mask:0xf bank_mask:0xf bound_ctrl:1
	v_mul_f32_e32 v84, v40, v26
	v_mul_f32_e32 v85, v41, v27
	v_add_f32_dpp v80, v80, v80 row_ror:8 row_mask:0xf bank_mask:0xf bound_ctrl:1
	v_mul_f32_e32 v82, v64, v82
	v_mul_f32_e32 v83, v65, v83
	v_add_f32_dpp v80, v80, v80 row_bcast:15 row_mask:0xa bank_mask:0xf
	v_mul_f32_e32 v84, v84, v82
	v_mul_f32_e32 v85, v85, v83
	v_add_f32_dpp v80, v80, v80 row_bcast:31 row_mask:0xc bank_mask:0xf
	s_nop 1
	v_readlane_b32 s20, v80, 63
	s_nop 2
	v_mov_b32_e32 v81, s20
	v_fmamk_f32 v81, v81, 0x3c000000, v241
	v_rsq_f32_e32 v81, v81
	s_nop 0
	v_mul_f32_e32 v84, v84, v81
	v_mul_f32_e32 v85, v85, v81
	v_cvt_pk_bf16_f32 v84, v84, v85
	global_store_dword v[2:3], v84, off offset:512
	s_waitcnt vmcnt(17)
	v_mul_f32_e32 v80, v42, v42
	v_mul_f32_e32 v82, 0xbfb8aa3b, v66
	v_fmac_f32_e32 v80, v43, v43
	v_mul_f32_e32 v83, 0xbfb8aa3b, v67
	v_exp_f32_e32 v82, v82
	v_exp_f32_e32 v83, v83
	v_add_f32_dpp v80, v80, v80 quad_perm:[1,0,3,2] row_mask:0xf bank_mask:0xf bound_ctrl:1
	v_add_f32_e32 v82, 1.0, v82
	v_add_f32_e32 v83, 1.0, v83
	v_add_f32_dpp v80, v80, v80 quad_perm:[2,3,0,1] row_mask:0xf bank_mask:0xf bound_ctrl:1
	v_rcp_f32_e32 v82, v82
	v_rcp_f32_e32 v83, v83
	v_add_f32_dpp v80, v80, v80 row_half_mirror row_mask:0xf bank_mask:0xf bound_ctrl:1
	v_mul_f32_e32 v84, v42, v26
	v_mul_f32_e32 v85, v43, v27
	v_add_f32_dpp v80, v80, v80 row_ror:8 row_mask:0xf bank_mask:0xf bound_ctrl:1
	v_mul_f32_e32 v82, v66, v82
	v_mul_f32_e32 v83, v67, v83
	v_add_f32_dpp v80, v80, v80 row_bcast:15 row_mask:0xa bank_mask:0xf
	v_mul_f32_e32 v84, v84, v82
	v_mul_f32_e32 v85, v85, v83
	v_add_f32_dpp v80, v80, v80 row_bcast:31 row_mask:0xc bank_mask:0xf
	s_nop 1
	v_readlane_b32 s20, v80, 63
	s_nop 2
	v_mov_b32_e32 v81, s20
	v_fmamk_f32 v81, v81, 0x3c000000, v241
	v_rsq_f32_e32 v81, v81
	s_nop 0
	v_mul_f32_e32 v84, v84, v81
	v_mul_f32_e32 v85, v85, v81
	v_cvt_pk_bf16_f32 v84, v84, v85
	global_store_dword v[2:3], v84, off offset:768
	s_waitcnt vmcnt(16)
; DI unsigned pk2(float lo, float hi) { f32x2 v = {lo, hi}; bf16x2_t b = __builtin_convertvector(v, bf16x2_t); return __builtin_bit_cast(unsigned, b); }
; DI float frsq(float x) { return __builtin_amdgcn_rsqf(x); }
; DI float siluf_(float x) { return x * frcp(1.f + __expf(-x)); }
; DI void gdn_post_row(const float* ORAW, const float* P, const float* norm_g, bf16* YCAT, long tg, int lane) {
;     const f32x2 g2 = *(const f32x2*)(norm_g + 2 * lane);
; #pragma unroll 4
;     for (int vh = 0; vh < 12; ++vh) {
;         const f32x2 o = *(const f32x2*)(ORAW + tg * MIXW + vh * 128 + 2 * lane);
;         const f32x2 z = *(const f32x2*)(P + tg * 5376 + 3072 + vh * 128 + 2 * lane);
;         const float rs = frsq(wave_sum(o.x * o.x + o.y * o.y) * (1.f / 128.f) + 1e-6f);
;         *(unsigned*)(YCAT + tg * DM + vh * 128 + 2 * lane) = pk2(o.x * rs * g2.x * siluf_(z.x), o.y * rs * g2.y * siluf_(z.y));
;     }
; }
	v_mul_f32_e32 v80, v44, v44
	v_mul_f32_e32 v82, 0xbfb8aa3b, v68
	v_fmac_f32_e32 v80, v45, v45
	v_mul_f32_e32 v83, 0xbfb8aa3b, v69
	v_exp_f32_e32 v82, v82
	v_exp_f32_e32 v83, v83
	v_add_f32_dpp v80, v80, v80 quad_perm:[1,0,3,2] row_mask:0xf bank_mask:0xf bound_ctrl:1
	v_add_f32_e32 v82, 1.0, v82
	v_add_f32_e32 v83, 1.0, v83
	v_add_f32_dpp v80, v80, v80 quad_perm:[2,3,0,1] row_mask:0xf bank_mask:0xf bound_ctrl:1
	v_rcp_f32_e32 v82, v82
	v_rcp_f32_e32 v83, v83
	v_add_f32_dpp v80, v80, v80 row_half_mirror row_mask:0xf bank_mask:0xf bound_ctrl:1
	v_mul_f32_e32 v84, v44, v26
	v_mul_f32_e32 v85, v45, v27
	v_add_f32_dpp v80, v80, v80 row_ror:8 row_mask:0xf bank_mask:0xf bound_ctrl:1
	v_mul_f32_e32 v82, v68, v82
	v_mul_f32_e32 v83, v69, v83
	v_add_f32_dpp v80, v80, v80 row_bcast:15 row_mask:0xa bank_mask:0xf
	v_mul_f32_e32 v84, v84, v82
	v_mul_f32_e32 v85, v85, v83
	v_add_f32_dpp v80, v80, v80 row_bcast:31 row_mask:0xc bank_mask:0xf
	s_nop 1
	v_readlane_b32 s20, v80, 63
	s_nop 2
	v_mov_b32_e32 v81, s20
	v_fmamk_f32 v81, v81, 0x3c000000, v241
	v_rsq_f32_e32 v81, v81
	s_nop 0
	v_mul_f32_e32 v84, v84, v81
	v_mul_f32_e32 v85, v85, v81
	v_cvt_pk_bf16_f32 v84, v84, v85
	global_store_dword v[2:3], v84, off offset:1024
	s_waitcnt vmcnt(15)
	v_mul_f32_e32 v80, v46, v46
	v_mul_f32_e32 v82, 0xbfb8aa3b, v70
	v_fmac_f32_e32 v80, v47, v47
	v_mul_f32_e32 v83, 0xbfb8aa3b, v71
	v_exp_f32_e32 v82, v82
	v_exp_f32_e32 v83, v83
	v_add_f32_dpp v80, v80, v80 quad_perm:[1,0,3,2] row_mask:0xf bank_mask:0xf bound_ctrl:1
	v_add_f32_e32 v82, 1.0, v82
	v_add_f32_e32 v83, 1.0, v83
	v_add_f32_dpp v80, v80, v80 quad_perm:[2,3,0,1] row_mask:0xf bank_mask:0xf bound_ctrl:1
	v_rcp_f32_e32 v82, v82
	v_rcp_f32_e32 v83, v83
	v_add_f32_dpp v80, v80, v80 row_half_mirror row_mask:0xf bank_mask:0xf bound_ctrl:1
	v_mul_f32_e32 v84, v46, v26
	v_mul_f32_e32 v85, v47, v27
	v_add_f32_dpp v80, v80, v80 row_ror:8 row_mask:0xf bank_mask:0xf bound_ctrl:1
	v_mul_f32_e32 v82, v70, v82
	v_mul_f32_e32 v83, v71, v83
	v_add_f32_dpp v80, v80, v80 row_bcast:15 row_mask:0xa bank_mask:0xf
	v_mul_f32_e32 v84, v84, v82
	v_mul_f32_e32 v85, v85, v83
	v_add_f32_dpp v80, v80, v80 row_bcast:31 row_mask:0xc bank_mask:0xf
	s_nop 1
	v_readlane_b32 s20, v80, 63
	s_nop 2
	v_mov_b32_e32 v81, s20
	v_fmamk_f32 v81, v81, 0x3c000000, v241
	v_rsq_f32_e32 v81, v81
	s_nop 0
	v_mul_f32_e32 v84, v84, v81
	v_mul_f32_e32 v85, v85, v81
	v_cvt_pk_bf16_f32 v84, v84, v85
	global_store_dword v[2:3], v84, off offset:1280
	s_waitcnt vmcnt(14)
	v_mul_f32_e32 v80, v48, v48
	v_mul_f32_e32 v82, 0xbfb8aa3b, v72
	v_fmac_f32_e32 v80, v49, v49
	v_mul_f32_e32 v83, 0xbfb8aa3b, v73
	v_exp_f32_e32 v82, v82
	v_exp_f32_e32 v83, v83
	v_add_f32_dpp v80, v80, v80 quad_perm:[1,0,3,2] row_mask:0xf bank_mask:0xf bound_ctrl:1
	v_add_f32_e32 v82, 1.0, v82
	v_add_f32_e32 v83, 1.0, v83
	v_add_f32_dpp v80, v80, v80 quad_perm:[2,3,0,1] row_mask:0xf bank_mask:0xf bound_ctrl:1
	v_rcp_f32_e32 v82, v82
	v_rcp_f32_e32 v83, v83
	v_add_f32_dpp v80, v80, v80 row_half_mirror row_mask:0xf bank_mask:0xf bound_ctrl:1
	v_mul_f32_e32 v84, v48, v26
	v_mul_f32_e32 v85, v49, v27
	v_add_f32_dpp v80, v80, v80 row_ror:8 row_mask:0xf bank_mask:0xf bound_ctrl:1
	v_mul_f32_e32 v82, v72, v82
	v_mul_f32_e32 v83, v73, v83
	v_add_f32_dpp v80, v80, v80 row_bcast:15 row_mask:0xa bank_mask:0xf
	v_mul_f32_e32 v84, v84, v82
	v_mul_f32_e32 v85, v85, v83
	v_add_f32_dpp v80, v80, v80 row_bcast:31 row_mask:0xc bank_mask:0xf
	s_nop 1
	v_readlane_b32 s20, v80, 63
	s_nop 2
	v_mov_b32_e32 v81, s20
	v_fmamk_f32 v81, v81, 0x3c000000, v241
	v_rsq_f32_e32 v81, v81
	s_nop 0
	v_mul_f32_e32 v84, v84, v81
	v_mul_f32_e32 v85, v85, v81
	v_cvt_pk_bf16_f32 v84, v84, v85
	global_store_dword v[2:3], v84, off offset:1536
	s_waitcnt vmcnt(13)
; DI unsigned pk2(float lo, float hi) { f32x2 v = {lo, hi}; bf16x2_t b = __builtin_convertvector(v, bf16x2_t); return __builtin_bit_cast(unsigned, b); }
; DI float frsq(float x) { return __builtin_amdgcn_rsqf(x); }
; DI float siluf_(float x) { return x * frcp(1.f + __expf(-x)); }
; DI void gdn_post_row(const float* ORAW, const float* P, const float* norm_g, bf16* YCAT, long tg, int lane) {
;     const f32x2 g2 = *(const f32x2*)(norm_g + 2 * lane);
; #pragma unroll 4
;     for (int vh = 0; vh < 12; ++vh) {
;         const f32x2 o = *(const f32x2*)(ORAW + tg * MIXW + vh * 128 + 2 * lane);
;         const f32x2 z = *(const f32x2*)(P + tg * 5376 + 3072 + vh * 128 + 2 * lane);
;         const float rs = frsq(wave_sum(o.x * o.x + o.y * o.y) * (1.f / 128.f) + 1e-6f);
;         *(unsigned*)(YCAT + tg * DM + vh * 128 + 2 * lane) = pk2(o.x * rs * g2.x * siluf_(z.x), o.y * rs * g2.y * siluf_(z.y));
;     }
; }
; DI void phase_gdn_post(const Ctx& c) {
;     const float* ng = INP(29);
;     for (long m = c.gw; m < T; m += c.NGW) gdn_post_row(c.ORAW, c.P, ng, c.YCAT, m, c.lane);
; }
	v_mul_f32_e32 v80, v50, v50
	v_mul_f32_e32 v82, 0xbfb8aa3b, v74
	v_fmac_f32_e32 v80, v51, v51
	v_mul_f32_e32 v83, 0xbfb8aa3b, v75
	v_exp_f32_e32 v82, v82
	v_exp_f32_e32 v83, v83
	v_add_f32_dpp v80, v80, v80 quad_perm:[1,0,3,2] row_mask:0xf bank_mask:0xf bound_ctrl:1
	v_add_f32_e32 v82, 1.0, v82
	v_add_f32_e32 v83, 1.0, v83
	v_add_f32_dpp v80, v80, v80 quad_perm:[2,3,0,1] row_mask:0xf bank_mask:0xf bound_ctrl:1
	v_rcp_f32_e32 v82, v82
	v_rcp_f32_e32 v83, v83
	v_add_f32_dpp v80, v80, v80 row_half_mirror row_mask:0xf bank_mask:0xf bound_ctrl:1
	v_mul_f32_e32 v84, v50, v26
	v_mul_f32_e32 v85, v51, v27
	v_add_f32_dpp v80, v80, v80 row_ror:8 row_mask:0xf bank_mask:0xf bound_ctrl:1
	v_mul_f32_e32 v82, v74, v82
	v_mul_f32_e32 v83, v75, v83
	v_add_f32_dpp v80, v80, v80 row_bcast:15 row_mask:0xa bank_mask:0xf
	v_mul_f32_e32 v84, v84, v82
	v_mul_f32_e32 v85, v85, v83
	v_add_f32_dpp v80, v80, v80 row_bcast:31 row_mask:0xc bank_mask:0xf
	s_nop 1
	v_readlane_b32 s20, v80, 63
	s_nop 2
	v_mov_b32_e32 v81, s20
	v_fmamk_f32 v81, v81, 0x3c000000, v241
	v_rsq_f32_e32 v81, v81
	s_nop 0
	v_mul_f32_e32 v84, v84, v81
	v_mul_f32_e32 v85, v85, v81
	v_cvt_pk_bf16_f32 v84, v84, v85
	global_store_dword v[2:3], v84, off offset:1792
	s_waitcnt vmcnt(12)
	v_mul_f32_e32 v80, v52, v52
	v_mul_f32_e32 v82, 0xbfb8aa3b, v76
	v_fmac_f32_e32 v80, v53, v53
	v_mul_f32_e32 v83, 0xbfb8aa3b, v77
	v_exp_f32_e32 v82, v82
	v_exp_f32_e32 v83, v83
	v_add_f32_dpp v80, v80, v80 quad_perm:[1,0,3,2] row_mask:0xf bank_mask:0xf bound_ctrl:1
	v_add_f32_e32 v82, 1.0, v82
	v_add_f32_e32 v83, 1.0, v83
	v_add_f32_dpp v80, v80, v80 quad_perm:[2,3,0,1] row_mask:0xf bank_mask:0xf bound_ctrl:1
	v_rcp_f32_e32 v82, v82
	v_rcp_f32_e32 v83, v83
	v_add_f32_dpp v80, v80, v80 row_half_mirror row_mask:0xf bank_mask:0xf bound_ctrl:1
	v_mul_f32_e32 v84, v52, v26
	v_mul_f32_e32 v85, v53, v27
	v_add_f32_dpp v80, v80, v80 row_ror:8 row_mask:0xf bank_mask:0xf bound_ctrl:1
	v_mul_f32_e32 v82, v76, v82
	v_mul_f32_e32 v83, v77, v83
	v_add_f32_dpp v80, v80, v80 row_bcast:15 row_mask:0xa bank_mask:0xf
	v_mul_f32_e32 v84, v84, v82
	v_mul_f32_e32 v85, v85, v83
	v_add_f32_dpp v80, v80, v80 row_bcast:31 row_mask:0xc bank_mask:0xf
	s_nop 1
	v_readlane_b32 s20, v80, 63
	s_nop 2
	v_mov_b32_e32 v81, s20
	v_fmamk_f32 v81, v81, 0x3c000000, v241
	v_rsq_f32_e32 v81, v81
	s_nop 0
	v_mul_f32_e32 v84, v84, v81
	v_mul_f32_e32 v85, v85, v81
	v_cvt_pk_bf16_f32 v84, v84, v85
	global_store_dword v[2:3], v84, off offset:2048
	s_waitcnt vmcnt(11)
	v_mul_f32_e32 v80, v54, v54
	v_mul_f32_e32 v82, 0xbfb8aa3b, v78
	v_fmac_f32_e32 v80, v55, v55
	v_mul_f32_e32 v83, 0xbfb8aa3b, v79
	v_exp_f32_e32 v82, v82
	v_exp_f32_e32 v83, v83
	v_add_f32_dpp v80, v80, v80 quad_perm:[1,0,3,2] row_mask:0xf bank_mask:0xf bound_ctrl:1
	v_add_f32_e32 v82, 1.0, v82
	v_add_f32_e32 v83, 1.0, v83
	v_add_f32_dpp v80, v80, v80 quad_perm:[2,3,0,1] row_mask:0xf bank_mask:0xf bound_ctrl:1
	v_rcp_f32_e32 v82, v82
	v_rcp_f32_e32 v83, v83
	v_add_f32_dpp v80, v80, v80 row_half_mirror row_mask:0xf bank_mask:0xf bound_ctrl:1
	v_mul_f32_e32 v84, v54, v26
	v_mul_f32_e32 v85, v55, v27
	v_add_f32_dpp v80, v80, v80 row_ror:8 row_mask:0xf bank_mask:0xf bound_ctrl:1
	v_mul_f32_e32 v82, v78, v82
	v_mul_f32_e32 v83, v79, v83
	v_add_f32_dpp v80, v80, v80 row_bcast:15 row_mask:0xa bank_mask:0xf
	v_mul_f32_e32 v84, v84, v82
	v_mul_f32_e32 v85, v85, v83
	v_add_f32_dpp v80, v80, v80 row_bcast:31 row_mask:0xc bank_mask:0xf
	s_nop 1
	v_readlane_b32 s20, v80, 63
	s_nop 2
	v_mov_b32_e32 v81, s20
	v_fmamk_f32 v81, v81, 0x3c000000, v241
	v_rsq_f32_e32 v81, v81
	s_nop 0
	v_mul_f32_e32 v84, v84, v81
	v_mul_f32_e32 v85, v85, v81
	v_cvt_pk_bf16_f32 v84, v84, v85
	global_store_dword v[2:3], v84, off offset:2304
	s_add_u32 s4, s4, s6
	s_addc_u32 s5, s5, s7
	v_mov_b64_e32 v[8:9], 0x4000
	v_cmp_lt_i64_e32 vcc, s[4:5], v[8:9]
	v_lshl_add_u64 v[2:3], v[2:3], 0, s[8:9]
	v_lshl_add_u64 v[4:5], v[4:5], 0, s[10:11]
	v_lshl_add_u64 v[6:7], v[6:7], 0, s[12:13]
	s_cbranch_vccnz .LBB0_1023
